# attention PV block: packed row-sum adds split into scalar v_add_f32 beside MFMAs
# speedup vs baseline: 1.0097x; 1.0005x over previous
; __device__ __forceinline__ void attn_unit(const Params& P, unsigned char* lds, int h, int qb) {
;     ...
;             lsum += ps0 + ps1;
.LBB0_884:
	s_bitcmp1_b32 s21, 0
	s_cselect_b32 s8, 0x2200, 0
	v_add_u32_e32 v142, s8, v250
	v_add_u32_e32 v143, 0x7800, v142
	v_add_u32_e32 v142, 0x6800, v142
	ds_read2_b64 v[112:115], v142 offset1:2
	ds_read2_b64 v[116:119], v143 offset0:32 offset1:34
	ds_read2_b64 v[120:123], v142 offset0:4 offset1:6
	ds_read2_b64 v[124:127], v143 offset0:36 offset1:38
	v_add_f32_e32 v14, v14, v128
	v_add_f32_e32 v15, v15, v129
	v_add_f32_e32 v14, v14, v130
	v_add_f32_e32 v15, v15, v131
	v_add_f32_e32 v14, v14, v132
	v_add_f32_e32 v15, v15, v133
	v_add_f32_e32 v14, v14, v134
	v_add_f32_e32 v15, v15, v135
	v_add_f32_e32 v14, v14, v136
	v_add_f32_e32 v15, v15, v137
	v_add_f32_e32 v14, v14, v138
	v_add_f32_e32 v15, v15, v139
	v_add_f32_e32 v14, v14, v140
	v_add_f32_e32 v15, v15, v141
	ds_read2_b64 v[128:131], v142 offset0:8 offset1:10
	ds_read2_b64 v[132:135], v143 offset0:40 offset1:42
	ds_read2_b64 v[136:139], v142 offset0:12 offset1:14
	s_waitcnt lgkmcnt(6)
	v_mfma_f32_32x32x16_bf16 v[48:63], v[112:115], v[2:5], v[48:63]
	v_max3_f32 v140, v16, v17, v80
	v_max3_f32 v141, v81, v18, v19
	v_add_f32_e32 v14, v14, v96
	v_add_f32_e32 v15, v15, v97
	s_waitcnt lgkmcnt(5)
	v_mfma_f32_32x32x16_bf16 v[32:47], v[116:119], v[2:5], v[32:47]
	ds_read2_b64 v[112:115], v143 offset0:44 offset1:46
	v_max3_f32 v140, v140, v82, v83
	v_add_f32_e32 v14, v14, v98
	v_add_f32_e32 v15, v15, v99
	v_max3_f32 v141, v141, v20, v21
	s_waitcnt lgkmcnt(5)
	v_mfma_f32_32x32x16_bf16 v[48:63], v[120:123], v[6:9], v[48:63]
	v_add_f32_e32 v14, v14, v100
	v_add_f32_e32 v15, v15, v101
	v_max3_f32 v140, v140, v84, v85
	v_add_f32_e32 v14, v14, v102
	v_add_f32_e32 v15, v15, v103
	s_waitcnt lgkmcnt(4)
	v_mfma_f32_32x32x16_bf16 v[32:47], v[124:127], v[6:9], v[32:47]
	v_max3_f32 v141, v141, v22, v23
	v_add_f32_e32 v14, v14, v104
	v_add_f32_e32 v15, v15, v105
	v_max3_f32 v140, v140, v86, v87
	s_waitcnt lgkmcnt(3)
	v_mfma_f32_32x32x16_bf16 v[48:63], v[128:131], v[10:13], v[48:63]
	v_add_f32_e32 v14, v14, v106
	v_add_f32_e32 v15, v15, v107
	v_max3_f32 v141, v141, v24, v25
	v_add_f32_e32 v14, v14, v108
	v_add_f32_e32 v15, v15, v109
	s_waitcnt lgkmcnt(2)
	v_mfma_f32_32x32x16_bf16 v[32:47], v[132:135], v[10:13], v[32:47]
	v_max3_f32 v140, v140, v88, v89
	v_add_f32_e32 v14, v14, v110
	v_add_f32_e32 v15, v15, v111
	v_max3_f32 v141, v141, v26, v27
	s_waitcnt lgkmcnt(1)
	v_mfma_f32_32x32x16_bf16 v[48:63], v[136:139], v[180:183], v[48:63]
	v_max3_f32 v140, v140, v90, v91
	v_max3_f32 v141, v141, v28, v29
	v_max3_f32 v140, v140, v92, v93
	s_waitcnt lgkmcnt(0)
	v_mfma_f32_32x32x16_bf16 v[32:47], v[112:115], v[180:183], v[32:47]
	v_max3_f32 v141, v141, v30, v31
	v_max3_f32 v140, v140, v94, v95
	v_max_f32_e32 v98, v140, v141
	v_add_f32_e32 v96, v14, v15
	v_add_f32_e32 v236, v236, v96
	s_branch .LBB0_896
